# speedup vs baseline: 1.0170x; 1.0031x over previous
; __device__ __forceinline__ bf16_t f2bf(float v) { return (bf16_t)(cvt_pk_bf16(v, 0.f) & 0xffffu); }
; __device__ __forceinline__ float bflo(unsigned w) { return __uint_as_float(w << 16); }
; __device__ __forceinline__ float bfhi(unsigned w) { return __uint_as_float(w & 0xffff0000u); }
; __device__ __forceinline__ void gmlp_item(KP P, int ch, int h, unsigned char* lds) {
;     ...
;     const int t = threadIdx.x, w = t >> 6, lane = t & 63, r0 = ch * 128;
;     bf16_t uu16[8][4]; float bsv[4];
; #pragma unroll
;     for (int reg = 0; reg < 4; ++reg) {
;         const int tt = 16 * w + (lane >> 4) * 4 + reg;
;         bsv[reg] = bs[tt * 8 + h];
; #pragma unroll
;         for (int db = 0; db < 8; ++db) uu16[db][reg] = proj[(size_t)(r0 + tt) * 4096 + 1024 + h * 128 + db * 16 + (lane & 15)];
;     }
;     {
;         const int d0 = (t & 15) * 8;
;         float gg[8], bb[8];
; #pragma unroll
;         for (int j = 0; j < 8; ++j) { gg[j] = lng[h * 128 + d0 + j]; bb[j] = lnb[h * 128 + d0 + j]; }
; #pragma unroll
;         for (int i = 0; i < 4; ++i) {
;             const int s = (t >> 4) + 32 * i;
;             const u32x4 x = *(const u32x4*)(proj + (size_t)(r0 + s) * 4096 + 2048 + h * 128 + d0);
;             const f32x2 st = stats[s];
; #pragma unroll
;             for (int j = 0; j < 4; ++j) {
;                 T[(d0 + 2 * j) * 136 + s] = f2bf((bflo(x[j]) - st.x) * st.y * gg[2 * j] + bb[2 * j]);
;                 T[(d0 + 2 * j + 1) * 136 + s] = f2bf((bfhi(x[j]) - st.x) * st.y * gg[2 * j + 1] + bb[2 * j + 1]);
;             }
;         }
;     }
;     ...
;         for (int ks = 0; ks < 4; ++ks) Wa[ks] = *(const bf16x8*)(Wsb + ((size_t)h * 128 + 16 * w + l15) * 128 + ks * 32 + 8 * q);
.Lmy_deq_skip1:
	s_or_b64 exec, exec, s[100:101]
	v_cmp_gt_i32_e32 vcc, s56, v0
	s_and_saveexec_b64 s[48:49], vcc
	s_cbranch_execz .LBB0_1080
	v_cmp_lt_i32_e32 vcc, 47, v0
	s_and_saveexec_b64 s[12:13], vcc
	s_xor_b64 s[50:51], exec, s[12:13]
	s_cbranch_execz .LBB0_1092
	v_cmp_lt_u32_e32 vcc, s57, v0
	s_and_saveexec_b64 s[12:13], vcc
	s_xor_b64 s[52:53], exec, s[12:13]
	s_cbranch_execz .LBB0_1089
	v_and_b32_e32 v46, 7, v0
	v_lshlrev_b32_e32 v0, 4, v0
	v_and_b32_e32 v0, 0x7fffff80, v0
	v_lshlrev_b32_e32 v51, 7, v46
	v_add_lshl_u32 v236, v51, v141, 8
	v_mov_b32_e32 v237, v103
	v_lshl_add_u64 v[236:237], v[104:105], 0, v[236:237]
	global_load_dwordx4 v[240:243], v[236:237], off
	global_load_dwordx4 v[244:247], v[236:237], off offset:64
	global_load_dwordx4 v[248:251], v[236:237], off offset:128
	global_load_dwordx4 v[252:255], v[236:237], off offset:192
	v_add_u32_e32 v102, 0xffffdd00, v0
	v_or_b32_e32 v0, v51, v100
	v_lshlrev_b32_e32 v12, 2, v0
	v_or_b32_e32 v0, v102, v135
	v_lshlrev_b32_e32 v0, 13, v0
	v_mov_b32_e32 v1, v103
	v_lshl_add_u64 v[0:1], s[38:39], 0, v[0:1]
	v_lshlrev_b32_e32 v20, 8, v46
	v_mov_b32_e32 v21, v103
	s_load_dwordx4 s[12:15], s[30:31], 0x90
	s_load_dwordx2 s[54:55], s[30:31], 0xa8
	v_lshl_add_u64 v[0:1], v[0:1], 0, v[20:21]
	v_lshlrev_b32_e32 v22, 1, v100
	v_mov_b32_e32 v23, v103
	v_lshl_add_u64 v[0:1], v[0:1], 0, v[22:23]
	v_add_co_u32_e32 v0, vcc, s58, v0
	v_lshl_add_u64 v[24:25], v[102:103], 3, v[114:115]
	s_nop 0
	v_addc_co_u32_e32 v1, vcc, 0, v1, vcc
	global_load_dwordx4 v[16:19], v[0:1], off
	global_load_dwordx2 v[26:27], v[24:25], off
	s_waitcnt lgkmcnt(0)
	global_load_dwordx4 v[0:3], v12, s[12:13]
	global_load_dwordx4 v[4:7], v12, s[14:15]
	v_or_b32_e32 v8, v46, v128
	v_or_b32_e32 v9, v46, v130
	v_or_b32_e32 v10, v46, v132
	v_or_b32_e32 v11, v51, v166
	v_lshlrev_b32_e32 v30, 2, v8
	v_lshlrev_b32_e32 v31, 2, v9
	v_lshlrev_b32_e32 v33, 2, v10
	v_lshlrev_b32_e32 v29, 1, v11
	global_load_dwordx4 v[8:11], v12, s[12:13] offset:16
	s_nop 0
	global_load_dwordx4 v[12:15], v12, s[14:15] offset:16
	v_add_u32_e32 v28, v102, v101
	v_add_u32_e32 v32, v102, v129
	v_add_u32_e32 v36, v102, v131
	v_add_u32_e32 v38, v102, v133
	v_lshl_or_b32 v40, v28, 13, v29
	v_lshl_or_b32 v43, v32, 13, v29
	v_lshl_or_b32 v44, v36, 13, v29
	v_lshl_or_b32 v62, v38, 13, v29
	global_load_dwordx2 v[28:29], v[24:25], off offset:256
	global_load_dword v32, v30, s[54:55]
	s_nop 0
	global_load_dword v31, v31, s[54:55]
	s_nop 0
	global_load_dword v30, v33, s[54:55]
	v_or_b32_e32 v39, v102, v138
	v_mov_b32_e32 v35, v103
	v_mov_b32_e32 v37, v103
	v_or_b32_e32 v34, v46, v134
	v_lshlrev_b32_e32 v36, 13, v39
	v_lshl_add_u64 v[60:61], v[34:35], 2, s[54:55]
	v_lshl_add_u64 v[34:35], s[38:39], 0, v[36:37]
	v_lshl_add_u64 v[34:35], v[34:35], 0, v[20:21]
	v_lshl_add_u64 v[34:35], v[34:35], 0, v[22:23]
	v_add_co_u32_e32 v34, vcc, s58, v34
	global_load_ushort v66, v40, s[38:39] offset:2048
	global_load_ushort v67, v40, s[38:39] offset:2080
	global_load_ushort v68, v40, s[38:39] offset:2112
	global_load_ushort v52, v40, s[38:39] offset:2144
	global_load_ushort v49, v40, s[38:39] offset:2176
	global_load_ushort v42, v40, s[38:39] offset:2208
	global_load_ushort v38, v40, s[38:39] offset:2240
	global_load_ushort v33, v40, s[38:39] offset:2272
	v_addc_co_u32_e32 v35, vcc, 0, v35, vcc
	global_load_dwordx4 v[56:59], v[34:35], off
	global_load_ushort v69, v43, s[38:39] offset:2048
	global_load_ushort v70, v43, s[38:39] offset:2080
	global_load_ushort v71, v43, s[38:39] offset:2112
	global_load_ushort v55, v43, s[38:39] offset:2144
	global_load_ushort v50, v43, s[38:39] offset:2176
	global_load_ushort v45, v43, s[38:39] offset:2208
	global_load_ushort v41, v43, s[38:39] offset:2240
	global_load_ushort v35, v43, s[38:39] offset:2272
	global_load_ushort v72, v44, s[38:39] offset:2048
	global_load_ushort v73, v44, s[38:39] offset:2080
	global_load_ushort v74, v44, s[38:39] offset:2112
	global_load_ushort v53, v44, s[38:39] offset:2144
	global_load_ushort v47, v44, s[38:39] offset:2176
	global_load_ushort v43, v44, s[38:39] offset:2208
	global_load_ushort v39, v44, s[38:39] offset:2240
	global_load_ushort v36, v44, s[38:39] offset:2272
	global_load_dword v34, v[60:61], off
	s_waitcnt vmcnt(35)
	v_lshlrev_b32_e32 v37, 16, v16
	v_and_b32_e32 v16, 0xffff0000, v16
	s_waitcnt vmcnt(34)
	v_sub_f32_e32 v16, v16, v26
	v_sub_f32_e32 v37, v37, v26
	v_mul_f32_e32 v16, v27, v16
	v_mul_f32_e32 v37, v27, v37
	s_waitcnt vmcnt(32)
	v_fma_f32 v16, v1, v16, v5
	v_fma_f32 v37, v0, v37, v4
	v_cvt_pk_bf16_f32 v16, v16, s0
	v_cvt_pk_bf16_f32 v60, v37, s0
	global_load_ushort v75, v62, s[38:39] offset:2048
	global_load_ushort v76, v62, s[38:39] offset:2080
	global_load_ushort v77, v62, s[38:39] offset:2112
	global_load_ushort v54, v62, s[38:39] offset:2144
	global_load_ushort v48, v62, s[38:39] offset:2176
	global_load_ushort v44, v62, s[38:39] offset:2208
	global_load_ushort v40, v62, s[38:39] offset:2240
	global_load_ushort v37, v62, s[38:39] offset:2272
	ds_write_b16 v137, v16 offset:1296
	v_lshlrev_b32_e32 v16, 16, v17
	v_sub_f32_e32 v16, v16, v26
	v_mul_f32_e32 v16, v27, v16
	v_fma_f32 v16, v2, v16, v6
	v_cvt_pk_bf16_f32 v16, v16, s0
	ds_write_b16 v136, v16 offset:1568
	v_and_b32_e32 v16, 0xffff0000, v17
	v_sub_f32_e32 v16, v16, v26
	v_mul_f32_e32 v16, v27, v16
	v_fma_f32 v16, v3, v16, v7
	v_cvt_pk_bf16_f32 v16, v16, s0
	ds_write_b16 v137, v16 offset:1840
	v_lshlrev_b32_e32 v16, 16, v18
	v_sub_f32_e32 v16, v16, v26
	v_mul_f32_e32 v16, v27, v16
	s_waitcnt vmcnt(38)
; __device__ __forceinline__ bf16_t f2bf(float v) { return (bf16_t)(cvt_pk_bf16(v, 0.f) & 0xffffu); }
; __device__ __forceinline__ float bflo(unsigned w) { return __uint_as_float(w << 16); }
; __device__ __forceinline__ float bfhi(unsigned w) { return __uint_as_float(w & 0xffff0000u); }
; __device__ __forceinline__ void gmlp_item(KP P, int ch, int h, unsigned char* lds) {
;     ...
;     {
;         const int d0 = (t & 15) * 8;
;         float gg[8], bb[8];
; #pragma unroll
;         for (int j = 0; j < 8; ++j) { gg[j] = lng[h * 128 + d0 + j]; bb[j] = lnb[h * 128 + d0 + j]; }
; #pragma unroll
;         for (int i = 0; i < 4; ++i) {
;             const int s = (t >> 4) + 32 * i;
;             const u32x4 x = *(const u32x4*)(proj + (size_t)(r0 + s) * 4096 + 2048 + h * 128 + d0);
;             const f32x2 st = stats[s];
; #pragma unroll
;             for (int j = 0; j < 4; ++j) {
;                 T[(d0 + 2 * j) * 136 + s] = f2bf((bflo(x[j]) - st.x) * st.y * gg[2 * j] + bb[2 * j]);
;                 T[(d0 + 2 * j + 1) * 136 + s] = f2bf((bfhi(x[j]) - st.x) * st.y * gg[2 * j + 1] + bb[2 * j + 1]);
;             }
;         }
;     }
;     __syncthreads();
	v_fma_f32 v16, v8, v16, v12
	v_cvt_pk_bf16_f32 v78, v16, s0
	v_or_b32_e32 v16, v102, v139
	v_lshlrev_b32_e32 v16, 13, v16
	v_mov_b32_e32 v17, v103
	v_lshl_add_u64 v[16:17], s[38:39], 0, v[16:17]
	v_lshl_add_u64 v[16:17], v[16:17], 0, v[20:21]
	v_lshl_add_u64 v[16:17], v[16:17], 0, v[22:23]
	v_add_co_u32_e32 v16, vcc, s58, v16
	ds_write_b16 v136, v60 offset:1024
	s_nop 0
	v_addc_co_u32_e32 v17, vcc, 0, v17, vcc
	global_load_dwordx4 v[60:63], v[16:17], off
	global_load_dwordx2 v[64:65], v[24:25], off offset:512
	v_and_b32_e32 v16, 0xffff0000, v18
	v_sub_f32_e32 v16, v16, v26
	v_mul_f32_e32 v16, v27, v16
	v_fma_f32 v16, v9, v16, v13
	v_cvt_pk_bf16_f32 v16, v16, s0
	ds_write_b16 v137, v16 offset:2384
	v_lshlrev_b32_e32 v16, 16, v19
	v_sub_f32_e32 v16, v16, v26
	v_mul_f32_e32 v16, v27, v16
	v_fma_f32 v16, v10, v16, v14
	v_cvt_pk_bf16_f32 v16, v16, s0
	ds_write_b16 v136, v16 offset:2656
	v_and_b32_e32 v16, 0xffff0000, v19
	v_sub_f32_e32 v16, v16, v26
	v_mul_f32_e32 v16, v27, v16
	v_fma_f32 v16, v11, v16, v15
	v_cvt_pk_bf16_f32 v16, v16, s0
	ds_write_b16 v137, v16 offset:2928
	s_waitcnt vmcnt(27)
	v_lshlrev_b32_e32 v16, 16, v56
	v_sub_f32_e32 v16, v16, v28
	v_mul_f32_e32 v16, v29, v16
	v_fma_f32 v16, v0, v16, v4
	v_cvt_pk_bf16_f32 v16, v16, s0
	ds_write_b16 v136, v16 offset:1088
	v_and_b32_e32 v16, 0xffff0000, v56
	v_sub_f32_e32 v16, v16, v28
	v_mul_f32_e32 v16, v29, v16
	v_fma_f32 v16, v1, v16, v5
	v_cvt_pk_bf16_f32 v16, v16, s0
	ds_write_b16 v137, v16 offset:1360
	v_lshlrev_b32_e32 v16, 16, v57
	v_sub_f32_e32 v16, v16, v28
	v_mul_f32_e32 v16, v29, v16
	v_fma_f32 v16, v2, v16, v6
	v_cvt_pk_bf16_f32 v26, v16, s0
	v_add_lshl_u32 v16, v102, v140, 13
	v_mov_b32_e32 v17, v103
	v_lshl_add_u64 v[16:17], s[38:39], 0, v[16:17]
	v_lshl_add_u64 v[16:17], v[16:17], 0, v[20:21]
	v_lshl_add_u64 v[16:17], v[16:17], 0, v[22:23]
	v_add_co_u32_e32 v16, vcc, s58, v16
	global_load_dwordx2 v[24:25], v[24:25], off offset:768
	s_nop 0
	v_addc_co_u32_e32 v17, vcc, 0, v17, vcc
	global_load_dwordx4 v[16:19], v[16:17], off
	v_and_b32_e32 v20, 0xffff0000, v57
	v_sub_f32_e32 v20, v20, v28
	v_mul_f32_e32 v20, v29, v20
	v_fma_f32 v20, v3, v20, v7
	v_cvt_pk_bf16_f32 v20, v20, s0
	ds_write_b16 v137, v20 offset:1904
	v_lshlrev_b32_e32 v20, 16, v58
	v_sub_f32_e32 v20, v20, v28
	v_mul_f32_e32 v20, v29, v20
	v_fma_f32 v20, v8, v20, v12
	v_cvt_pk_bf16_f32 v20, v20, s0
	ds_write_b16 v136, v20 offset:2176
	v_and_b32_e32 v20, 0xffff0000, v58
	v_sub_f32_e32 v20, v20, v28
	v_mul_f32_e32 v20, v29, v20
	v_fma_f32 v20, v9, v20, v13
	v_cvt_pk_bf16_f32 v20, v20, s0
	ds_write_b16 v137, v20 offset:2448
	v_lshlrev_b32_e32 v20, 16, v59
	v_sub_f32_e32 v20, v20, v28
	v_mul_f32_e32 v20, v29, v20
	v_fma_f32 v20, v10, v20, v14
	v_cvt_pk_bf16_f32 v20, v20, s0
	ds_write_b16 v136, v20 offset:2720
	v_and_b32_e32 v20, 0xffff0000, v59
	v_sub_f32_e32 v20, v20, v28
	v_mul_f32_e32 v20, v29, v20
	v_fma_f32 v20, v11, v20, v15
	v_cvt_pk_bf16_f32 v20, v20, s0
	ds_write_b16 v137, v20 offset:2992
	ds_write_b16 v136, v78 offset:2112
	ds_write_b16 v136, v26 offset:1632
	s_waitcnt vmcnt(3)
	v_lshlrev_b32_e32 v20, 16, v60
	s_waitcnt vmcnt(2)
	v_sub_f32_e32 v20, v20, v64
	v_mul_f32_e32 v20, v65, v20
	v_fma_f32 v20, v0, v20, v4
	v_cvt_pk_bf16_f32 v20, v20, s0
	ds_write_b16 v136, v20 offset:1152
	v_and_b32_e32 v20, 0xffff0000, v60
	v_sub_f32_e32 v20, v20, v64
	v_mul_f32_e32 v20, v65, v20
	v_fma_f32 v20, v1, v20, v5
	v_cvt_pk_bf16_f32 v20, v20, s0
	ds_write_b16 v137, v20 offset:1424
	v_lshlrev_b32_e32 v20, 16, v61
	v_sub_f32_e32 v20, v20, v64
	v_mul_f32_e32 v20, v65, v20
	v_fma_f32 v20, v2, v20, v6
	v_cvt_pk_bf16_f32 v20, v20, s0
	ds_write_b16 v136, v20 offset:1696
	v_and_b32_e32 v20, 0xffff0000, v61
	v_sub_f32_e32 v20, v20, v64
	v_mul_f32_e32 v20, v65, v20
	v_fma_f32 v20, v3, v20, v7
	v_cvt_pk_bf16_f32 v20, v20, s0
	ds_write_b16 v137, v20 offset:1968
	v_lshlrev_b32_e32 v20, 16, v62
	v_sub_f32_e32 v20, v20, v64
	v_mul_f32_e32 v20, v65, v20
	v_fma_f32 v20, v8, v20, v12
	v_cvt_pk_bf16_f32 v20, v20, s0
	ds_write_b16 v136, v20 offset:2240
	v_and_b32_e32 v20, 0xffff0000, v62
	v_sub_f32_e32 v20, v20, v64
	v_mul_f32_e32 v20, v65, v20
	v_fma_f32 v20, v9, v20, v13
	v_cvt_pk_bf16_f32 v20, v20, s0
	ds_write_b16 v137, v20 offset:2512
	v_lshlrev_b32_e32 v20, 16, v63
	v_sub_f32_e32 v20, v20, v64
	v_mul_f32_e32 v20, v65, v20
	v_fma_f32 v20, v10, v20, v14
	v_cvt_pk_bf16_f32 v20, v20, s0
	ds_write_b16 v136, v20 offset:2784
	v_and_b32_e32 v20, 0xffff0000, v63
	v_sub_f32_e32 v20, v20, v64
	v_mul_f32_e32 v20, v65, v20
	v_fma_f32 v20, v11, v20, v15
	v_cvt_pk_bf16_f32 v20, v20, s0
	ds_write_b16 v137, v20 offset:3056
	s_waitcnt vmcnt(0)
	v_lshlrev_b32_e32 v20, 16, v16
	v_sub_f32_e32 v20, v20, v24
	v_mul_f32_e32 v20, v25, v20
	v_fma_f32 v0, v0, v20, v4
	v_cvt_pk_bf16_f32 v0, v0, s0
	ds_write_b16 v136, v0 offset:1216
	v_and_b32_e32 v0, 0xffff0000, v16
	v_sub_f32_e32 v0, v0, v24
	v_mul_f32_e32 v0, v25, v0
	v_fma_f32 v0, v1, v0, v5
	v_cvt_pk_bf16_f32 v0, v0, s0
	ds_write_b16 v137, v0 offset:1488
	v_lshlrev_b32_e32 v0, 16, v17
	v_sub_f32_e32 v0, v0, v24
	v_mul_f32_e32 v0, v25, v0
	v_fma_f32 v0, v2, v0, v6
	v_cvt_pk_bf16_f32 v0, v0, s0
	ds_write_b16 v136, v0 offset:1760
	v_and_b32_e32 v0, 0xffff0000, v17
	v_sub_f32_e32 v0, v0, v24
	v_mul_f32_e32 v0, v25, v0
	v_fmac_f32_e32 v7, v3, v0
	v_cvt_pk_bf16_f32 v0, v7, s0
	ds_write_b16 v137, v0 offset:2032
	v_lshlrev_b32_e32 v0, 16, v18
	v_sub_f32_e32 v0, v0, v24
	v_mul_f32_e32 v0, v25, v0
	v_fma_f32 v0, v8, v0, v12
	v_cvt_pk_bf16_f32 v0, v0, s0
	ds_write_b16 v136, v0 offset:2304
	v_and_b32_e32 v0, 0xffff0000, v18
	v_sub_f32_e32 v0, v0, v24
	v_mul_f32_e32 v0, v25, v0
	v_fma_f32 v0, v9, v0, v13
	v_cvt_pk_bf16_f32 v0, v0, s0
	ds_write_b16 v137, v0 offset:2576
	v_lshlrev_b32_e32 v0, 16, v19
	v_sub_f32_e32 v0, v0, v24
	v_mul_f32_e32 v0, v25, v0
	v_fma_f32 v0, v10, v0, v14
	v_cvt_pk_bf16_f32 v0, v0, s0
	ds_write_b16 v136, v0 offset:2848
	v_and_b32_e32 v0, 0xffff0000, v19
	v_sub_f32_e32 v0, v0, v24
	v_mul_f32_e32 v0, v25, v0
	v_fmac_f32_e32 v15, v11, v0
	v_cvt_pk_bf16_f32 v0, v15, s0
	ds_write_b16 v137, v0 offset:3120
	v_add_lshl_u32 v0, v51, v141, 8
	v_mov_b32_e32 v1, v103
	v_lshl_add_u64 v[24:25], v[104:105], 0, v[0:1]
	s_waitcnt lgkmcnt(0)
	s_barrier
; __device__ __forceinline__ bf16_t f2bf(float v) { return (bf16_t)(cvt_pk_bf16(v, 0.f) & 0xffffu); }
; __device__ __forceinline__ float bf2f(bf16_t b) { return __uint_as_float(((unsigned)b) << 16); }
; __device__ __forceinline__ size_t tl(int r, int c, int K) { return ((size_t)(r >> 8) * (size_t)(K >> 6) + (size_t)(c >> 6)) * 16384 + (size_t)((r & 255) << 6) + (size_t)(c & 63); }
; #define MFMA16(a, b, c) __builtin_amdgcn_mfma_f32_16x16x32_bf16((a), (b), (c), 0, 0, 0)
; __device__ __forceinline__ void gmlp_item(KP P, int ch, int h, unsigned char* lds) {
;     ...
;         bf16x8 Wa[4];
; #pragma unroll
;         for (int ks = 0; ks < 4; ++ks) Wa[ks] = *(const bf16x8*)(Wsb + ((size_t)h * 128 + 16 * w + l15) * 128 + ks * 32 + 8 * q);
; #pragma unroll
;         for (int db = 0; db < 8; ++db) {
;             f32x4 acc = (f32x4){0.f, 0.f, 0.f, 0.f};
; #pragma unroll
;             for (int ks = 0; ks < 4; ++ks) acc = MFMA16(Wa[ks], *(const bf16x8*)(T + (db * 16 + l15) * 136 + ks * 32 + 8 * q), acc);
; #pragma unroll
;             for (int reg = 0; reg < 4; ++reg) {
;                 const int tt = 16 * w + q * 4 + reg, c = h * 128 + db * 16 + l15;
;                 gm[tl(r0 + tt, c, 1024)] = f2bf(bf2f(uu16[db][reg]) * (acc[reg] + bsv[reg]));
;             }
;         }
	ds_read_b128 v[8:11], v152 offset:1024
	ds_read_b128 v[16:19], v152 offset:1088
	v_mov_b32_e32 v29, v103
	v_lshlrev_b32_e32 v60, 1, v166
	v_mov_b32_e32 v61, v103
	s_waitcnt vmcnt(2) lgkmcnt(1)
	v_mfma_f32_16x16x32_bf16 v[20:23], v[240:243], v[8:11], 0
	s_waitcnt vmcnt(2) lgkmcnt(0)
	v_mfma_f32_16x16x32_bf16 v[16:19], v[244:247], v[16:19], v[20:23]
	s_nop 4
	ds_read_b128 v[20:23], v152 offset:1152
	ds_read_b128 v[24:27], v152 offset:1216
	ds_read_b128 v[56:59], v152 offset:5504
	s_waitcnt vmcnt(1) lgkmcnt(2)
	v_mfma_f32_16x16x32_bf16 v[16:19], v[248:251], v[20:23], v[16:19]
	v_add_u32_e32 v22, v142, v102
	v_lshlrev_b32_e32 v20, 16, v66
	s_waitcnt vmcnt(0) lgkmcnt(1)
	v_mfma_f32_16x16x32_bf16 v[16:19], v[252:255], v[24:27], v[16:19]
	ds_read_b128 v[24:27], v152 offset:5440
	s_nop 6
	v_add_f32_e32 v16, v32, v16
	v_mul_f32_e32 v16, v16, v20
	v_lshlrev_b32_e32 v20, 11, v22
	v_and_b32_e32 v20, 0x3f80000, v20
	v_lshl_or_b32 v102, v46, 16, v20
	v_lshlrev_b32_e32 v22, 7, v22
	v_lshl_add_u64 v[20:21], s[40:41], 0, v[102:103]
	v_and_b32_e32 v28, 0x7e00, v22
	v_lshl_add_u64 v[20:21], v[20:21], 0, v[28:29]
	v_lshl_add_u64 v[62:63], v[20:21], 0, v[60:61]
	ds_read_b128 v[20:23], v152 offset:5376
	v_cvt_pk_bf16_f32 v16, v16, s0
	s_waitcnt lgkmcnt(0)
	v_mfma_f32_16x16x32_bf16 v[20:23], v[240:243], v[20:23], 0
	global_store_short v[62:63], v16, off
	v_lshlrev_b32_e32 v16, 16, v69
	v_add_f32_e32 v17, v31, v17
	v_mul_f32_e32 v16, v17, v16
	v_cvt_pk_bf16_f32 v16, v16, s0
	global_store_short v[62:63], v16, off offset:128
	v_lshlrev_b32_e32 v16, 16, v72
	v_add_f32_e32 v17, v30, v18
	v_mfma_f32_16x16x32_bf16 v[20:23], v[244:247], v[24:27], v[20:23]
	v_mul_f32_e32 v16, v17, v16
	v_cvt_pk_bf16_f32 v16, v16, s0
	global_store_short v[62:63], v16, off offset:256
	v_add_f32_e32 v25, v34, v19
	ds_read_b128 v[16:19], v152 offset:5568
	v_mfma_f32_16x16x32_bf16 v[20:23], v[248:251], v[56:59], v[20:23]
	v_lshlrev_b32_e32 v24, 16, v75
	v_mul_f32_e32 v24, v25, v24
	v_cvt_pk_bf16_f32 v24, v24, s0
	s_waitcnt lgkmcnt(0)
	v_mfma_f32_16x16x32_bf16 v[16:19], v[252:255], v[16:19], v[20:23]
	global_store_short v[62:63], v24, off offset:384
	ds_read_b128 v[24:27], v152 offset:9792
	ds_read_b128 v[56:59], v152 offset:9856
	v_lshlrev_b32_e32 v20, 16, v67
	v_or_b32_e32 v102, 0x8000, v102
	s_nop 2
	v_add_f32_e32 v16, v32, v16
	v_mul_f32_e32 v16, v16, v20
	ds_read_b128 v[20:23], v152 offset:9728
	v_cvt_pk_bf16_f32 v16, v16, s0
	s_waitcnt lgkmcnt(0)
	v_mfma_f32_16x16x32_bf16 v[20:23], v[240:243], v[20:23], 0
	global_store_short v[62:63], v16, off offset:32
	v_lshlrev_b32_e32 v16, 16, v70
	v_add_f32_e32 v17, v31, v17
	v_mul_f32_e32 v16, v17, v16
	v_cvt_pk_bf16_f32 v16, v16, s0
	global_store_short v[62:63], v16, off offset:160
	v_lshlrev_b32_e32 v16, 16, v73
	v_add_f32_e32 v17, v30, v18
	v_mfma_f32_16x16x32_bf16 v[20:23], v[244:247], v[24:27], v[20:23]
	v_mul_f32_e32 v16, v17, v16
	v_cvt_pk_bf16_f32 v16, v16, s0
	global_store_short v[62:63], v16, off offset:288
	v_add_f32_e32 v25, v34, v19
	ds_read_b128 v[16:19], v152 offset:9920
	v_mfma_f32_16x16x32_bf16 v[20:23], v[248:251], v[56:59], v[20:23]
	v_lshlrev_b32_e32 v24, 16, v76
	v_mul_f32_e32 v24, v25, v24
	v_cvt_pk_bf16_f32 v24, v24, s0
	s_waitcnt lgkmcnt(0)
	v_mfma_f32_16x16x32_bf16 v[16:19], v[252:255], v[16:19], v[20:23]
	global_store_short v[62:63], v24, off offset:416
	ds_read_b128 v[24:27], v152 offset:14144
	ds_read_b128 v[56:59], v152 offset:14208
	v_lshlrev_b32_e32 v20, 16, v68
	s_nop 3
	v_add_f32_e32 v16, v32, v16
	v_mul_f32_e32 v16, v16, v20
	ds_read_b128 v[20:23], v152 offset:14080
	v_cvt_pk_bf16_f32 v16, v16, s0
	s_waitcnt lgkmcnt(0)
	v_mfma_f32_16x16x32_bf16 v[20:23], v[240:243], v[20:23], 0
	global_store_short v[62:63], v16, off offset:64
	v_lshlrev_b32_e32 v16, 16, v71
	v_add_f32_e32 v17, v31, v17
	v_mul_f32_e32 v16, v17, v16
	v_cvt_pk_bf16_f32 v16, v16, s0
	global_store_short v[62:63], v16, off offset:192
	v_lshlrev_b32_e32 v16, 16, v74
	v_add_f32_e32 v17, v30, v18
	v_mfma_f32_16x16x32_bf16 v[20:23], v[244:247], v[24:27], v[20:23]
	v_mul_f32_e32 v16, v17, v16
	v_cvt_pk_bf16_f32 v16, v16, s0
	global_store_short v[62:63], v16, off offset:320
	v_add_f32_e32 v25, v34, v19
	ds_read_b128 v[16:19], v152 offset:14272
	v_mfma_f32_16x16x32_bf16 v[20:23], v[248:251], v[56:59], v[20:23]
	v_lshlrev_b32_e32 v24, 16, v77
	v_mul_f32_e32 v24, v25, v24
	v_cvt_pk_bf16_f32 v24, v24, s0
	s_waitcnt lgkmcnt(0)
	v_mfma_f32_16x16x32_bf16 v[16:19], v[252:255], v[16:19], v[20:23]
	global_store_short v[62:63], v24, off offset:448
	ds_read_b128 v[24:27], v152 offset:18496
	ds_read_b128 v[56:59], v152 offset:18560
	v_lshlrev_b32_e32 v20, 16, v52
	s_nop 3
	v_add_f32_e32 v16, v32, v16
	v_mul_f32_e32 v16, v16, v20
	ds_read_b128 v[20:23], v152 offset:18432
	v_cvt_pk_bf16_f32 v16, v16, s0
	s_waitcnt lgkmcnt(0)
; __device__ __forceinline__ bf16_t f2bf(float v) { return (bf16_t)(cvt_pk_bf16(v, 0.f) & 0xffffu); }
; __device__ __forceinline__ float bf2f(bf16_t b) { return __uint_as_float(((unsigned)b) << 16); }
; __device__ __forceinline__ size_t tl(int r, int c, int K) { return ((size_t)(r >> 8) * (size_t)(K >> 6) + (size_t)(c >> 6)) * 16384 + (size_t)((r & 255) << 6) + (size_t)(c & 63); }
; #define MFMA16(a, b, c) __builtin_amdgcn_mfma_f32_16x16x32_bf16((a), (b), (c), 0, 0, 0)
; __device__ __forceinline__ void gmlp_item(KP P, int ch, int h, unsigned char* lds) {
;     ...
; #pragma unroll
;         for (int db = 0; db < 8; ++db) {
;             f32x4 acc = (f32x4){0.f, 0.f, 0.f, 0.f};
; #pragma unroll
;             for (int ks = 0; ks < 4; ++ks) acc = MFMA16(Wa[ks], *(const bf16x8*)(T + (db * 16 + l15) * 136 + ks * 32 + 8 * q), acc);
; #pragma unroll
;             for (int reg = 0; reg < 4; ++reg) {
;                 const int tt = 16 * w + q * 4 + reg, c = h * 128 + db * 16 + l15;
;                 gm[tl(r0 + tt, c, 1024)] = f2bf(bf2f(uu16[db][reg]) * (acc[reg] + bsv[reg]));
;             }
;         }
;     }
;     __syncthreads();
	v_mfma_f32_16x16x32_bf16 v[20:23], v[240:243], v[20:23], 0
	global_store_short v[62:63], v16, off offset:96
	v_lshlrev_b32_e32 v16, 16, v55
	v_add_f32_e32 v17, v31, v17
	v_mul_f32_e32 v16, v17, v16
	v_cvt_pk_bf16_f32 v16, v16, s0
	global_store_short v[62:63], v16, off offset:224
	v_lshlrev_b32_e32 v16, 16, v53
	v_add_f32_e32 v17, v30, v18
	v_mfma_f32_16x16x32_bf16 v[20:23], v[244:247], v[24:27], v[20:23]
	v_mul_f32_e32 v16, v17, v16
	v_cvt_pk_bf16_f32 v16, v16, s0
	global_store_short v[62:63], v16, off offset:352
	v_add_f32_e32 v25, v34, v19
	ds_read_b128 v[16:19], v152 offset:18624
	v_mfma_f32_16x16x32_bf16 v[20:23], v[248:251], v[56:59], v[20:23]
	v_lshlrev_b32_e32 v24, 16, v54
	v_mul_f32_e32 v24, v25, v24
	v_cvt_pk_bf16_f32 v24, v24, s0
	s_waitcnt lgkmcnt(0)
	v_mfma_f32_16x16x32_bf16 v[16:19], v[252:255], v[16:19], v[20:23]
	global_store_short v[62:63], v24, off offset:480
	ds_read_b128 v[24:27], v152 offset:22848
	s_nop 0
	v_lshlrev_b32_e32 v20, 16, v49
	s_nop 3
	v_add_f32_e32 v16, v32, v16
	v_mul_f32_e32 v16, v16, v20
	v_lshl_add_u64 v[20:21], s[40:41], 0, v[102:103]
	v_lshl_add_u64 v[20:21], v[20:21], 0, v[28:29]
	v_lshl_add_u64 v[28:29], v[20:21], 0, v[60:61]
	ds_read_b128 v[20:23], v152 offset:22784
	v_cvt_pk_bf16_f32 v16, v16, s0
	s_waitcnt lgkmcnt(0)
	v_mfma_f32_16x16x32_bf16 v[20:23], v[240:243], v[20:23], 0
	global_store_short v[28:29], v16, off
	v_lshlrev_b32_e32 v16, 16, v50
	v_add_f32_e32 v17, v31, v17
	v_mul_f32_e32 v16, v17, v16
	v_cvt_pk_bf16_f32 v16, v16, s0
	ds_read_b128 v[50:53], v152 offset:22912
	global_store_short v[28:29], v16, off offset:128
	v_lshlrev_b32_e32 v16, 16, v47
	v_add_f32_e32 v17, v30, v18
	v_mfma_f32_16x16x32_bf16 v[20:23], v[244:247], v[24:27], v[20:23]
	v_mul_f32_e32 v16, v17, v16
	v_cvt_pk_bf16_f32 v16, v16, s0
	global_store_short v[28:29], v16, off offset:256
	v_add_f32_e32 v25, v34, v19
	ds_read_b128 v[16:19], v152 offset:22976
	s_waitcnt lgkmcnt(1)
	v_mfma_f32_16x16x32_bf16 v[20:23], v[248:251], v[50:53], v[20:23]
	v_lshlrev_b32_e32 v24, 16, v48
	v_mul_f32_e32 v24, v25, v24
	v_cvt_pk_bf16_f32 v24, v24, s0
	s_waitcnt lgkmcnt(0)
	v_mfma_f32_16x16x32_bf16 v[16:19], v[252:255], v[16:19], v[20:23]
	global_store_short v[28:29], v24, off offset:384
	ds_read_b128 v[24:27], v152 offset:27200
	ds_read_b128 v[46:49], v152 offset:27264
	v_lshlrev_b32_e32 v20, 16, v42
	s_nop 3
	v_add_f32_e32 v16, v32, v16
	v_mul_f32_e32 v16, v16, v20
	ds_read_b128 v[20:23], v152 offset:27136
	v_cvt_pk_bf16_f32 v16, v16, s0
	s_waitcnt lgkmcnt(0)
	v_mfma_f32_16x16x32_bf16 v[20:23], v[240:243], v[20:23], 0
	global_store_short v[28:29], v16, off offset:32
	v_lshlrev_b32_e32 v16, 16, v45
	v_add_f32_e32 v17, v31, v17
	v_mul_f32_e32 v16, v17, v16
	v_cvt_pk_bf16_f32 v16, v16, s0
	global_store_short v[28:29], v16, off offset:160
	v_lshlrev_b32_e32 v16, 16, v43
	v_add_f32_e32 v17, v30, v18
	v_mfma_f32_16x16x32_bf16 v[20:23], v[244:247], v[24:27], v[20:23]
	v_mul_f32_e32 v16, v17, v16
	v_cvt_pk_bf16_f32 v16, v16, s0
	global_store_short v[28:29], v16, off offset:288
	v_add_f32_e32 v25, v34, v19
	ds_read_b128 v[16:19], v152 offset:27328
	v_mfma_f32_16x16x32_bf16 v[20:23], v[248:251], v[46:49], v[20:23]
	v_lshlrev_b32_e32 v24, 16, v44
	v_mul_f32_e32 v24, v25, v24
	v_cvt_pk_bf16_f32 v24, v24, s0
	s_waitcnt lgkmcnt(0)
	v_mfma_f32_16x16x32_bf16 v[16:19], v[252:255], v[16:19], v[20:23]
	global_store_short v[28:29], v24, off offset:416
	ds_read_b128 v[24:27], v152 offset:31552
	s_nop 0
	v_lshlrev_b32_e32 v20, 16, v38
	s_nop 3
	v_add_f32_e32 v16, v32, v16
	v_mul_f32_e32 v16, v16, v20
	ds_read_b128 v[20:23], v152 offset:31488
	s_waitcnt lgkmcnt(0)
	v_mfma_f32_16x16x32_bf16 v[12:15], v[240:243], v[20:23], 0
	ds_read_b128 v[20:23], v152 offset:31616
	v_cvt_pk_bf16_f32 v16, v16, s0
	global_store_short v[28:29], v16, off offset:64
	v_mfma_f32_16x16x32_bf16 v[0:3], v[244:247], v[24:27], v[12:15]
	v_lshlrev_b32_e32 v16, 16, v41
	v_add_f32_e32 v17, v31, v17
	v_mul_f32_e32 v16, v17, v16
	s_nop 0
	ds_read_b128 v[12:15], v152 offset:31680
	s_waitcnt lgkmcnt(1)
	v_mfma_f32_16x16x32_bf16 v[0:3], v[248:251], v[20:23], v[0:3]
	v_cvt_pk_bf16_f32 v16, v16, s0
	global_store_short v[28:29], v16, off offset:192
	v_lshlrev_b32_e32 v16, 16, v39
	v_add_f32_e32 v17, v30, v18
	v_mul_f32_e32 v16, v17, v16
	v_cvt_pk_bf16_f32 v16, v16, s0
	s_waitcnt lgkmcnt(0)
	v_mfma_f32_16x16x32_bf16 v[0:3], v[252:255], v[12:15], v[0:3]
	global_store_short v[28:29], v16, off offset:320
	v_lshlrev_b32_e32 v16, 16, v40
	v_add_f32_e32 v17, v34, v19
	v_mul_f32_e32 v4, v17, v16
	v_cvt_pk_bf16_f32 v4, v4, s0
	global_store_short v[28:29], v4, off offset:448
	v_lshlrev_b32_e32 v4, 16, v33
	s_nop 0
	v_add_f32_e32 v0, v32, v0
	v_mul_f32_e32 v0, v0, v4
	v_cvt_pk_bf16_f32 v0, v0, s0
	global_store_short v[28:29], v0, off offset:96
	v_lshlrev_b32_e32 v0, 16, v35
	v_add_f32_e32 v1, v31, v1
	v_mul_f32_e32 v0, v1, v0
	v_cvt_pk_bf16_f32 v0, v0, s0
	global_store_short v[28:29], v0, off offset:224
	v_lshlrev_b32_e32 v0, 16, v36
	v_add_f32_e32 v1, v30, v2
	v_mul_f32_e32 v0, v1, v0
	v_cvt_pk_bf16_f32 v0, v0, s0
	global_store_short v[28:29], v0, off offset:352
	v_lshlrev_b32_e32 v0, 16, v37
	v_add_f32_e32 v1, v34, v3
	v_mul_f32_e32 v0, v1, v0
	v_cvt_pk_bf16_f32 v0, v0, s0
	global_store_short v[28:29], v0, off offset:480
	s_barrier
